# all edits combined; conversion routine tile stride taken from gridDim instead of a constant
# speedup vs baseline: 1.0084x; 1.0016x over previous
.LBB0_48:
	s_or_b64 exec, exec, s[4:5]
	s_cmp_gt_i32 s97, -1
	s_cselect_b64 s[76:77], -1, 0
	s_cmp_lt_i32 s97, s0
	s_cselect_b64 s[2:3], -1, 0
	s_and_b64 s[2:3], s[76:77], s[2:3]
	v_mov_b32_e32 v0, v204
	s_andn2_b64 vcc, exec, s[2:3]
	s_cbranch_vccnz .LBB0_64
	s_load_dwordx2 s[18:19], s[86:87], 0xb8
	s_waitcnt lgkmcnt(0)
	v_lshrrev_b32_e32 v0, 3, v204
	v_and_b32_e32 v1, 7, v204
	v_lshlrev_b32_e32 v1, 3, v1
	v_mul_u32_u24_e32 v2, 65, v0
	v_add_lshl_u32 v2, v2, v1, 2
	v_mul_u32_u24_e32 v4, 65, v1
	v_add_lshl_u32 v4, v4, v0, 2
	s_add_u32 s39, s97, 0
	s_mov_b32 s33, s39
	s_lshl_b32 s68, s22, 1
	s_mul_i32 s69, s22, 3
	s_lshl_b32 s21, s22, 2
	s_add_u32 s35, s33, 0
	s_cmp_lt_u32 s35, 896
	s_cselect_b32 s35, s35, s39
	s_mov_b64 s[64:65], s[16:17]
	s_mov_b32 s8, 3584
	s_mov_b32 s9, 0x4924925
	s_mov_b32 s12, 56
	s_movk_i32 s13, 0
	s_add_u32 s66, s18, 0x0
	s_addc_u32 s67, s19, 0
	s_movk_i32 s14, 1024
	s_mov_b32 s15, 1
	s_add_u32 s70, s10, 0
	s_addc_u32 s71, s11, 0
.Lcv_z_p0_c:
	s_sub_u32 s0, s35, s13
	s_mul_hi_u32 s1, s0, s9
	s_mul_i32 s2, s1, s12
	s_sub_u32 s2, s0, s2
	s_lshl_b32 s1, s1, 6
	s_lshl_b32 s2, s2, 6
	s_mul_i32 s3, s1, s8
	s_lshl_b32 s3, s3, 2
	s_add_u32 s64, s64, s3
	s_addc_u32 s65, s65, 0
	v_add_u32_e32 v5, s2, v1
	s_sub_u32 s4, s8, 8
	v_min_u32_e32 v5, s4, v5
	v_mad_u32_u24 v5, v0, s8, v5
	v_lshlrev_b32_e32 v5, 2, v5
	global_load_dwordx4 v[40:43], v5, s[64:65]
	global_load_dwordx4 v[44:47], v5, s[64:65] offset:16
	s_lshl_b32 s3, s1, 2
	s_add_u32 s70, s70, s3
	s_addc_u32 s71, s71, 0
	v_lshlrev_b32_e32 v6, 2, v0
	global_load_dword v48, v6, s[70:71]
	s_mul_i32 s3, s2, s14
	s_add_u32 s3, s3, s1
	s_lshl_b32 s3, s3, 1
	s_add_u32 s40, s66, s3
	s_addc_u32 s41, s67, 0
	s_mov_b32 s42, s14
	s_sub_u32 s43, s8, s2
	s_mov_b32 s44, s15
	s_add_u32 s35, s33, s22
	s_cmp_lt_u32 s35, 896
	s_cselect_b32 s35, s35, s39
	s_mov_b64 s[64:65], s[16:17]
	s_mov_b32 s8, 3584
	s_mov_b32 s9, 0x4924925
	s_mov_b32 s12, 56
	s_movk_i32 s13, 0
	s_add_u32 s66, s18, 0x0
	s_addc_u32 s67, s19, 0
	s_movk_i32 s14, 1024
	s_mov_b32 s15, 1
	s_add_u32 s70, s10, 0
	s_addc_u32 s71, s11, 0
.Lcv_z_p1_c:
	s_sub_u32 s0, s35, s13
	s_mul_hi_u32 s1, s0, s9
	s_mul_i32 s2, s1, s12
	s_sub_u32 s2, s0, s2
	s_lshl_b32 s1, s1, 6
	s_lshl_b32 s2, s2, 6
	s_mul_i32 s3, s1, s8
	s_lshl_b32 s3, s3, 2
	s_add_u32 s64, s64, s3
	s_addc_u32 s65, s65, 0
	v_add_u32_e32 v5, s2, v1
	s_sub_u32 s4, s8, 8
	v_min_u32_e32 v5, s4, v5
	v_mad_u32_u24 v5, v0, s8, v5
	v_lshlrev_b32_e32 v5, 2, v5
	global_load_dwordx4 v[50:53], v5, s[64:65]
	global_load_dwordx4 v[54:57], v5, s[64:65] offset:16
	s_lshl_b32 s3, s1, 2
	s_add_u32 s70, s70, s3
	s_addc_u32 s71, s71, 0
	v_lshlrev_b32_e32 v6, 2, v0
	global_load_dword v58, v6, s[70:71]
	s_mul_i32 s3, s2, s14
	s_add_u32 s3, s3, s1
	s_lshl_b32 s3, s3, 1
	s_add_u32 s46, s66, s3
	s_addc_u32 s47, s67, 0
	s_mov_b32 s48, s14
	s_sub_u32 s49, s8, s2
	s_mov_b32 s50, s15
	s_add_u32 s35, s33, s68
	s_cmp_lt_u32 s35, 896
	s_cselect_b32 s35, s35, s39
	s_mov_b64 s[64:65], s[16:17]
	s_mov_b32 s8, 3584
	s_mov_b32 s9, 0x4924925
	s_mov_b32 s12, 56
	s_movk_i32 s13, 0
	s_add_u32 s66, s18, 0x0
	s_addc_u32 s67, s19, 0
	s_movk_i32 s14, 1024
	s_mov_b32 s15, 1
	s_add_u32 s70, s10, 0
	s_addc_u32 s71, s11, 0
.Lcv_z_p2_c:
	s_sub_u32 s0, s35, s13
	s_mul_hi_u32 s1, s0, s9
	s_mul_i32 s2, s1, s12
	s_sub_u32 s2, s0, s2
	s_lshl_b32 s1, s1, 6
	s_lshl_b32 s2, s2, 6
	s_mul_i32 s3, s1, s8
	s_lshl_b32 s3, s3, 2
	s_add_u32 s64, s64, s3
	s_addc_u32 s65, s65, 0
	v_add_u32_e32 v5, s2, v1
	s_sub_u32 s4, s8, 8
	v_min_u32_e32 v5, s4, v5
	v_mad_u32_u24 v5, v0, s8, v5
	v_lshlrev_b32_e32 v5, 2, v5
	global_load_dwordx4 v[60:63], v5, s[64:65]
	global_load_dwordx4 v[64:67], v5, s[64:65] offset:16
	s_lshl_b32 s3, s1, 2
	s_add_u32 s70, s70, s3
	s_addc_u32 s71, s71, 0
	v_lshlrev_b32_e32 v6, 2, v0
	global_load_dword v68, v6, s[70:71]
	s_mul_i32 s3, s2, s14
	s_add_u32 s3, s3, s1
	s_lshl_b32 s3, s3, 1
	s_add_u32 s52, s66, s3
	s_addc_u32 s53, s67, 0
	s_mov_b32 s54, s14
	s_sub_u32 s55, s8, s2
	s_mov_b32 s56, s15
	s_add_u32 s35, s33, s69
	s_cmp_lt_u32 s35, 896
	s_cselect_b32 s35, s35, s39
	s_mov_b64 s[64:65], s[16:17]
	s_mov_b32 s8, 3584
	s_mov_b32 s9, 0x4924925
	s_mov_b32 s12, 56
	s_movk_i32 s13, 0
	s_add_u32 s66, s18, 0x0
	s_addc_u32 s67, s19, 0
	s_movk_i32 s14, 1024
	s_mov_b32 s15, 1
	s_add_u32 s70, s10, 0
	s_addc_u32 s71, s11, 0

.Lcv_z_loop:
	s_add_u32 s35, s33, 0
	s_cmp_ge_u32 s35, 896
	s_cbranch_scc1 .Lcv_z_exit
	s_add_u32 s34, s35, s21
	s_cmp_lt_u32 s34, 896
	s_cselect_b32 s34, s34, s39
	s_waitcnt vmcnt(13)
	v_cmp_gt_i32_e32 vcc, s43, v1
	s_cmp_eq_u32 s44, 0
	s_cbranch_scc0 .Lcv_z_l0_hs
	v_mov_b32_e32 v48, 1.0

.Lcv_z_l0n_c:
	s_sub_u32 s0, s34, s13
	s_mul_hi_u32 s1, s0, s9
	s_mul_i32 s2, s1, s12
	s_sub_u32 s2, s0, s2
	s_lshl_b32 s1, s1, 6
	s_lshl_b32 s2, s2, 6
	s_mul_i32 s3, s1, s8
	s_lshl_b32 s3, s3, 2
	s_add_u32 s64, s64, s3
	s_addc_u32 s65, s65, 0
	v_add_u32_e32 v5, s2, v1
	s_sub_u32 s4, s8, 8
	v_min_u32_e32 v5, s4, v5
	v_mad_u32_u24 v5, v0, s8, v5
	v_lshlrev_b32_e32 v5, 2, v5
	global_load_dwordx4 v[40:43], v5, s[64:65]
	global_load_dwordx4 v[44:47], v5, s[64:65] offset:16
	s_lshl_b32 s3, s1, 2
	s_add_u32 s70, s70, s3
	s_addc_u32 s71, s71, 0
	v_lshlrev_b32_e32 v6, 2, v0
	global_load_dword v48, v6, s[70:71]
	s_mul_i32 s3, s2, s14
	s_add_u32 s3, s3, s1
	s_lshl_b32 s3, s3, 1
	s_add_u32 s40, s66, s3
	s_addc_u32 s41, s67, 0
	s_mov_b32 s42, s14
	s_sub_u32 s43, s8, s2
	s_mov_b32 s44, s15
	s_waitcnt lgkmcnt(0)
	s_barrier
	ds_read_b32 v10, v4 offset:0
	ds_read_b32 v11, v4 offset:260
	ds_read_b32 v12, v4 offset:520
	ds_read_b32 v13, v4 offset:780
	ds_read_b32 v14, v4 offset:1040
	ds_read_b32 v15, v4 offset:1300
	ds_read_b32 v16, v4 offset:1560
	ds_read_b32 v17, v4 offset:1820
	v_mad_u32_u24 v7, v0, s38, v1
	v_lshlrev_b32_e32 v7, 1, v7
	s_waitcnt lgkmcnt(0)
	v_cvt_pk_bf16_f32 v18, v10, v11
	v_cvt_pk_bf16_f32 v19, v12, v13
	v_cvt_pk_bf16_f32 v20, v14, v15
	v_cvt_pk_bf16_f32 v21, v16, v17
	global_store_dwordx4 v7, v[18:21], s[36:37]
	s_add_u32 s35, s33, s22
	s_cmp_ge_u32 s35, 896
	s_cbranch_scc1 .Lcv_z_exit
	s_add_u32 s34, s35, s21
	s_cmp_lt_u32 s34, 896
	s_cselect_b32 s34, s34, s39
	s_waitcnt vmcnt(13)
	v_cmp_gt_i32_e32 vcc, s49, v1
	s_cmp_eq_u32 s50, 0
	s_cbranch_scc0 .Lcv_z_l1_hs
	v_mov_b32_e32 v58, 1.0

.Lcv_z_l1n_c:
	s_sub_u32 s0, s34, s13
	s_mul_hi_u32 s1, s0, s9
	s_mul_i32 s2, s1, s12
	s_sub_u32 s2, s0, s2
	s_lshl_b32 s1, s1, 6
	s_lshl_b32 s2, s2, 6
	s_mul_i32 s3, s1, s8
	s_lshl_b32 s3, s3, 2
	s_add_u32 s64, s64, s3
	s_addc_u32 s65, s65, 0
	v_add_u32_e32 v5, s2, v1
	s_sub_u32 s4, s8, 8
	v_min_u32_e32 v5, s4, v5
	v_mad_u32_u24 v5, v0, s8, v5
	v_lshlrev_b32_e32 v5, 2, v5
	global_load_dwordx4 v[50:53], v5, s[64:65]
	global_load_dwordx4 v[54:57], v5, s[64:65] offset:16
	s_lshl_b32 s3, s1, 2
	s_add_u32 s70, s70, s3
	s_addc_u32 s71, s71, 0
	v_lshlrev_b32_e32 v6, 2, v0
	global_load_dword v58, v6, s[70:71]
	s_mul_i32 s3, s2, s14
	s_add_u32 s3, s3, s1
	s_lshl_b32 s3, s3, 1
	s_add_u32 s46, s66, s3
	s_addc_u32 s47, s67, 0
	s_mov_b32 s48, s14
	s_sub_u32 s49, s8, s2
	s_mov_b32 s50, s15
	s_waitcnt lgkmcnt(0)
	s_barrier
	ds_read_b32 v10, v4 offset:16640
	ds_read_b32 v11, v4 offset:16900
	ds_read_b32 v12, v4 offset:17160
	ds_read_b32 v13, v4 offset:17420
	ds_read_b32 v14, v4 offset:17680
	ds_read_b32 v15, v4 offset:17940
	ds_read_b32 v16, v4 offset:18200
	ds_read_b32 v17, v4 offset:18460
	v_mad_u32_u24 v7, v0, s38, v1
	v_lshlrev_b32_e32 v7, 1, v7
	s_waitcnt lgkmcnt(0)
	v_cvt_pk_bf16_f32 v18, v10, v11
	v_cvt_pk_bf16_f32 v19, v12, v13
	v_cvt_pk_bf16_f32 v20, v14, v15
	v_cvt_pk_bf16_f32 v21, v16, v17
	global_store_dwordx4 v7, v[18:21], s[36:37]
	s_add_u32 s35, s33, s68
	s_cmp_ge_u32 s35, 896
	s_cbranch_scc1 .Lcv_z_exit
	s_add_u32 s34, s35, s21
	s_cmp_lt_u32 s34, 896
	s_cselect_b32 s34, s34, s39
	s_waitcnt vmcnt(13)
	v_cmp_gt_i32_e32 vcc, s55, v1
	s_cmp_eq_u32 s56, 0
	s_cbranch_scc0 .Lcv_z_l2_hs
	v_mov_b32_e32 v68, 1.0

.Lcv_z_l2n_c:
	s_sub_u32 s0, s34, s13
	s_mul_hi_u32 s1, s0, s9
	s_mul_i32 s2, s1, s12
	s_sub_u32 s2, s0, s2
	s_lshl_b32 s1, s1, 6
	s_lshl_b32 s2, s2, 6
	s_mul_i32 s3, s1, s8
	s_lshl_b32 s3, s3, 2
	s_add_u32 s64, s64, s3
	s_addc_u32 s65, s65, 0
	v_add_u32_e32 v5, s2, v1
	s_sub_u32 s4, s8, 8
	v_min_u32_e32 v5, s4, v5
	v_mad_u32_u24 v5, v0, s8, v5
	v_lshlrev_b32_e32 v5, 2, v5
	global_load_dwordx4 v[60:63], v5, s[64:65]
	global_load_dwordx4 v[64:67], v5, s[64:65] offset:16
	s_lshl_b32 s3, s1, 2
	s_add_u32 s70, s70, s3
	s_addc_u32 s71, s71, 0
	v_lshlrev_b32_e32 v6, 2, v0
	global_load_dword v68, v6, s[70:71]
	s_mul_i32 s3, s2, s14
	s_add_u32 s3, s3, s1
	s_lshl_b32 s3, s3, 1
	s_add_u32 s52, s66, s3
	s_addc_u32 s53, s67, 0
	s_mov_b32 s54, s14
	s_sub_u32 s55, s8, s2
	s_mov_b32 s56, s15
	s_waitcnt lgkmcnt(0)
	s_barrier
	ds_read_b32 v10, v4 offset:0
	ds_read_b32 v11, v4 offset:260
	ds_read_b32 v12, v4 offset:520
	ds_read_b32 v13, v4 offset:780
	ds_read_b32 v14, v4 offset:1040
	ds_read_b32 v15, v4 offset:1300
	ds_read_b32 v16, v4 offset:1560
	ds_read_b32 v17, v4 offset:1820
	v_mad_u32_u24 v7, v0, s38, v1
	v_lshlrev_b32_e32 v7, 1, v7
	s_waitcnt lgkmcnt(0)
	v_cvt_pk_bf16_f32 v18, v10, v11
	v_cvt_pk_bf16_f32 v19, v12, v13
	v_cvt_pk_bf16_f32 v20, v14, v15
	v_cvt_pk_bf16_f32 v21, v16, v17
	global_store_dwordx4 v7, v[18:21], s[36:37]
	s_add_u32 s35, s33, s69
	s_cmp_ge_u32 s35, 896
	s_cbranch_scc1 .Lcv_z_exit
	s_add_u32 s34, s35, s21
	s_cmp_lt_u32 s34, 896
	s_cselect_b32 s34, s34, s39
	s_waitcnt vmcnt(13)
	v_cmp_gt_i32_e32 vcc, s61, v1
	s_cmp_eq_u32 s62, 0
	s_cbranch_scc0 .Lcv_z_l3_hs
	v_mov_b32_e32 v78, 1.0

.Lcv_z_l3n_c:
	s_sub_u32 s0, s34, s13
	s_mul_hi_u32 s1, s0, s9
	s_mul_i32 s2, s1, s12
	s_sub_u32 s2, s0, s2
	s_lshl_b32 s1, s1, 6
	s_lshl_b32 s2, s2, 6
	s_mul_i32 s3, s1, s8
	s_lshl_b32 s3, s3, 2
	s_add_u32 s64, s64, s3
	s_addc_u32 s65, s65, 0
	v_add_u32_e32 v5, s2, v1
	s_sub_u32 s4, s8, 8
	v_min_u32_e32 v5, s4, v5
	v_mad_u32_u24 v5, v0, s8, v5
	v_lshlrev_b32_e32 v5, 2, v5
	global_load_dwordx4 v[70:73], v5, s[64:65]
	global_load_dwordx4 v[74:77], v5, s[64:65] offset:16
	s_lshl_b32 s3, s1, 2
	s_add_u32 s70, s70, s3
	s_addc_u32 s71, s71, 0
	v_lshlrev_b32_e32 v6, 2, v0
	global_load_dword v78, v6, s[70:71]
	s_mul_i32 s3, s2, s14
	s_add_u32 s3, s3, s1
	s_lshl_b32 s3, s3, 1
	s_add_u32 s58, s66, s3
	s_addc_u32 s59, s67, 0
	s_mov_b32 s60, s14
	s_sub_u32 s61, s8, s2
	s_mov_b32 s62, s15
	s_waitcnt lgkmcnt(0)
	s_barrier
	ds_read_b32 v10, v4 offset:16640
	ds_read_b32 v11, v4 offset:16900
	ds_read_b32 v12, v4 offset:17160
	ds_read_b32 v13, v4 offset:17420
	ds_read_b32 v14, v4 offset:17680
	ds_read_b32 v15, v4 offset:17940
	ds_read_b32 v16, v4 offset:18200
	ds_read_b32 v17, v4 offset:18460
	v_mad_u32_u24 v7, v0, s38, v1
	v_lshlrev_b32_e32 v7, 1, v7
	s_waitcnt lgkmcnt(0)
	v_cvt_pk_bf16_f32 v18, v10, v11
	v_cvt_pk_bf16_f32 v19, v12, v13
	v_cvt_pk_bf16_f32 v20, v14, v15
	v_cvt_pk_bf16_f32 v21, v16, v17
	global_store_dwordx4 v7, v[18:21], s[36:37]
	s_add_u32 s33, s33, s21
	s_branch .Lcv_z_loop

.LBB0_116:
	s_or_b64 exec, exec, s[4:5]
	s_mov_b64 s[0:1], s[86:87]
	s_waitcnt lgkmcnt(0)
	s_barrier
	s_load_dwordx4 s[24:27], s[0:1], 0x8
	s_load_dwordx8 s[12:19], s[0:1], 0x20
	s_load_dwordx2 s[28:29], s[0:1], 0x88
	s_load_dwordx2 s[10:11], s[0:1], 0xb8
	s_bitcmp1_b32 s97, 0
	s_cselect_b64 s[30:31], -1, 0
	s_and_b64 vcc, exec, s[30:31]
	s_cbranch_vccnz .LBB0_152
	s_waitcnt lgkmcnt(0)
	v_lshrrev_b32_e32 v0, 3, v204
	v_and_b32_e32 v1, 7, v204
	v_lshlrev_b32_e32 v1, 3, v1
	v_mul_u32_u24_e32 v2, 65, v0
	v_add_lshl_u32 v2, v2, v1, 2
	v_mul_u32_u24_e32 v4, 65, v1
	v_add_lshl_u32 v4, v4, v0, 2
	s_add_u32 s39, s97, 896
	s_mov_b32 s33, s39
	s_lshl_b32 s68, s22, 1
	s_mul_i32 s69, s22, 3
	s_lshl_b32 s21, s22, 2
	s_add_u32 s35, s33, 0
	s_cmp_lt_u32 s35, 4032
	s_cselect_b32 s35, s35, s39
	s_cmp_lt_u32 s35, 1152
	s_cbranch_scc0 .Lcv_a_p0_m1
	s_mov_b64 s[64:65], s[18:19]
	s_mov_b32 s5, 1024
	s_mov_b32 s6, 0x10000000
	s_mov_b32 s7, 16
	s_movk_i32 s8, 896
	s_add_u32 s66, s10, 0x700000
	s_addc_u32 s67, s11, 0
	s_movk_i32 s9, 1024
	s_mov_b32 s20, 0
	s_mov_b64 s[70:71], s[24:25]
	s_branch .Lcv_a_p0_c

.Lcv_a_p0_c:
	s_sub_u32 s0, s35, s8
	s_mul_hi_u32 s1, s0, s6
	s_mul_i32 s2, s1, s7
	s_sub_u32 s2, s0, s2
	s_lshl_b32 s1, s1, 6
	s_lshl_b32 s2, s2, 6
	s_mul_i32 s3, s1, s5
	s_lshl_b32 s3, s3, 2
	s_add_u32 s64, s64, s3
	s_addc_u32 s65, s65, 0
	v_add_u32_e32 v5, s2, v1
	s_sub_u32 s4, s5, 8
	v_min_u32_e32 v5, s4, v5
	v_mad_u32_u24 v5, v0, s5, v5
	v_lshlrev_b32_e32 v5, 2, v5
	global_load_dwordx4 v[40:43], v5, s[64:65]
	global_load_dwordx4 v[44:47], v5, s[64:65] offset:16
	s_lshl_b32 s3, s1, 2
	s_add_u32 s70, s70, s3
	s_addc_u32 s71, s71, 0
	v_lshlrev_b32_e32 v6, 2, v0
	global_load_dword v48, v6, s[70:71]
	s_mul_i32 s3, s2, s9
	s_add_u32 s3, s3, s1
	s_lshl_b32 s3, s3, 1
	s_add_u32 s40, s66, s3
	s_addc_u32 s41, s67, 0
	s_mov_b32 s42, s9
	s_sub_u32 s43, s5, s2
	s_mov_b32 s44, s20
	s_add_u32 s35, s33, s22
	s_cmp_lt_u32 s35, 4032
	s_cselect_b32 s35, s35, s39
	s_cmp_lt_u32 s35, 1152
	s_cbranch_scc0 .Lcv_a_p1_m1
	s_mov_b64 s[64:65], s[18:19]
	s_mov_b32 s5, 1024
	s_mov_b32 s6, 0x10000000
	s_mov_b32 s7, 16
	s_movk_i32 s8, 896
	s_add_u32 s66, s10, 0x700000
	s_addc_u32 s67, s11, 0
	s_movk_i32 s9, 1024
	s_mov_b32 s20, 0
	s_mov_b64 s[70:71], s[24:25]
	s_branch .Lcv_a_p1_c

.Lcv_a_p1_c:
	s_sub_u32 s0, s35, s8
	s_mul_hi_u32 s1, s0, s6
	s_mul_i32 s2, s1, s7
	s_sub_u32 s2, s0, s2
	s_lshl_b32 s1, s1, 6
	s_lshl_b32 s2, s2, 6
	s_mul_i32 s3, s1, s5
	s_lshl_b32 s3, s3, 2
	s_add_u32 s64, s64, s3
	s_addc_u32 s65, s65, 0
	v_add_u32_e32 v5, s2, v1
	s_sub_u32 s4, s5, 8
	v_min_u32_e32 v5, s4, v5
	v_mad_u32_u24 v5, v0, s5, v5
	v_lshlrev_b32_e32 v5, 2, v5
	global_load_dwordx4 v[50:53], v5, s[64:65]
	global_load_dwordx4 v[54:57], v5, s[64:65] offset:16
	s_lshl_b32 s3, s1, 2
	s_add_u32 s70, s70, s3
	s_addc_u32 s71, s71, 0
	v_lshlrev_b32_e32 v6, 2, v0
	global_load_dword v58, v6, s[70:71]
	s_mul_i32 s3, s2, s9
	s_add_u32 s3, s3, s1
	s_lshl_b32 s3, s3, 1
	s_add_u32 s46, s66, s3
	s_addc_u32 s47, s67, 0
	s_mov_b32 s48, s9
	s_sub_u32 s49, s5, s2
	s_mov_b32 s50, s20
	s_add_u32 s35, s33, s68
	s_cmp_lt_u32 s35, 4032
	s_cselect_b32 s35, s35, s39
	s_cmp_lt_u32 s35, 1152
	s_cbranch_scc0 .Lcv_a_p2_m1
	s_mov_b64 s[64:65], s[18:19]
	s_mov_b32 s5, 1024
	s_mov_b32 s6, 0x10000000
	s_mov_b32 s7, 16
	s_movk_i32 s8, 896
	s_add_u32 s66, s10, 0x700000
	s_addc_u32 s67, s11, 0
	s_movk_i32 s9, 1024
	s_mov_b32 s20, 0
	s_mov_b64 s[70:71], s[24:25]
	s_branch .Lcv_a_p2_c

.Lcv_a_p2_c:
	s_sub_u32 s0, s35, s8
	s_mul_hi_u32 s1, s0, s6
	s_mul_i32 s2, s1, s7
	s_sub_u32 s2, s0, s2
	s_lshl_b32 s1, s1, 6
	s_lshl_b32 s2, s2, 6
	s_mul_i32 s3, s1, s5
	s_lshl_b32 s3, s3, 2
	s_add_u32 s64, s64, s3
	s_addc_u32 s65, s65, 0
	v_add_u32_e32 v5, s2, v1
	s_sub_u32 s4, s5, 8
	v_min_u32_e32 v5, s4, v5
	v_mad_u32_u24 v5, v0, s5, v5
	v_lshlrev_b32_e32 v5, 2, v5
	global_load_dwordx4 v[60:63], v5, s[64:65]
	global_load_dwordx4 v[64:67], v5, s[64:65] offset:16
	s_lshl_b32 s3, s1, 2
	s_add_u32 s70, s70, s3
	s_addc_u32 s71, s71, 0
	v_lshlrev_b32_e32 v6, 2, v0
	global_load_dword v68, v6, s[70:71]
	s_mul_i32 s3, s2, s9
	s_add_u32 s3, s3, s1
	s_lshl_b32 s3, s3, 1
	s_add_u32 s52, s66, s3
	s_addc_u32 s53, s67, 0
	s_mov_b32 s54, s9
	s_sub_u32 s55, s5, s2
	s_mov_b32 s56, s20
	s_add_u32 s35, s33, s69
	s_cmp_lt_u32 s35, 4032
	s_cselect_b32 s35, s35, s39
	s_cmp_lt_u32 s35, 1152
	s_cbranch_scc0 .Lcv_a_p3_m1
	s_mov_b64 s[64:65], s[18:19]
	s_mov_b32 s5, 1024
	s_mov_b32 s6, 0x10000000
	s_mov_b32 s7, 16
	s_movk_i32 s8, 896
	s_add_u32 s66, s10, 0x700000
	s_addc_u32 s67, s11, 0
	s_movk_i32 s9, 1024
	s_mov_b32 s20, 0
	s_mov_b64 s[70:71], s[24:25]
	s_branch .Lcv_a_p3_c

.Lcv_a_loop:
	s_add_u32 s35, s33, 0
	s_cmp_ge_u32 s35, 4032
	s_cbranch_scc1 .Lcv_a_exit
	s_add_u32 s34, s35, s21
	s_cmp_lt_u32 s34, 4032
	s_cselect_b32 s34, s34, s39
	s_waitcnt vmcnt(13)
	v_cmp_gt_i32_e32 vcc, s43, v1
	s_cmp_eq_u32 s44, 0
	s_cbranch_scc0 .Lcv_a_l0_hs
	v_mov_b32_e32 v48, 1.0

.Lcv_a_l0n_c:
	s_sub_u32 s0, s34, s8
	s_mul_hi_u32 s1, s0, s6
	s_mul_i32 s2, s1, s7
	s_sub_u32 s2, s0, s2
	s_lshl_b32 s1, s1, 6
	s_lshl_b32 s2, s2, 6
	s_mul_i32 s3, s1, s5
	s_lshl_b32 s3, s3, 2
	s_add_u32 s64, s64, s3
	s_addc_u32 s65, s65, 0
	v_add_u32_e32 v5, s2, v1
	s_sub_u32 s4, s5, 8
	v_min_u32_e32 v5, s4, v5
	v_mad_u32_u24 v5, v0, s5, v5
	v_lshlrev_b32_e32 v5, 2, v5
	global_load_dwordx4 v[40:43], v5, s[64:65]
	global_load_dwordx4 v[44:47], v5, s[64:65] offset:16
	s_lshl_b32 s3, s1, 2
	s_add_u32 s70, s70, s3
	s_addc_u32 s71, s71, 0
	v_lshlrev_b32_e32 v6, 2, v0
	global_load_dword v48, v6, s[70:71]
	s_mul_i32 s3, s2, s9
	s_add_u32 s3, s3, s1
	s_lshl_b32 s3, s3, 1
	s_add_u32 s40, s66, s3
	s_addc_u32 s41, s67, 0
	s_mov_b32 s42, s9
	s_sub_u32 s43, s5, s2
	s_mov_b32 s44, s20
	s_waitcnt lgkmcnt(0)
	s_barrier
	ds_read_b32 v10, v4 offset:0
	ds_read_b32 v11, v4 offset:260
	ds_read_b32 v12, v4 offset:520
	ds_read_b32 v13, v4 offset:780
	ds_read_b32 v14, v4 offset:1040
	ds_read_b32 v15, v4 offset:1300
	ds_read_b32 v16, v4 offset:1560
	ds_read_b32 v17, v4 offset:1820
	v_mad_u32_u24 v7, v0, s38, v1
	v_lshlrev_b32_e32 v7, 1, v7
	s_waitcnt lgkmcnt(0)
	v_cvt_pk_bf16_f32 v18, v10, v11
	v_cvt_pk_bf16_f32 v19, v12, v13
	v_cvt_pk_bf16_f32 v20, v14, v15
	v_cvt_pk_bf16_f32 v21, v16, v17
	global_store_dwordx4 v7, v[18:21], s[36:37]
	s_add_u32 s35, s33, s22
	s_cmp_ge_u32 s35, 4032
	s_cbranch_scc1 .Lcv_a_exit
	s_add_u32 s34, s35, s21
	s_cmp_lt_u32 s34, 4032
	s_cselect_b32 s34, s34, s39
	s_waitcnt vmcnt(13)
	v_cmp_gt_i32_e32 vcc, s49, v1
	s_cmp_eq_u32 s50, 0
	s_cbranch_scc0 .Lcv_a_l1_hs
	v_mov_b32_e32 v58, 1.0

.Lcv_a_l1n_c:
	s_sub_u32 s0, s34, s8
	s_mul_hi_u32 s1, s0, s6
	s_mul_i32 s2, s1, s7
	s_sub_u32 s2, s0, s2
	s_lshl_b32 s1, s1, 6
	s_lshl_b32 s2, s2, 6
	s_mul_i32 s3, s1, s5
	s_lshl_b32 s3, s3, 2
	s_add_u32 s64, s64, s3
	s_addc_u32 s65, s65, 0
	v_add_u32_e32 v5, s2, v1
	s_sub_u32 s4, s5, 8
	v_min_u32_e32 v5, s4, v5
	v_mad_u32_u24 v5, v0, s5, v5
	v_lshlrev_b32_e32 v5, 2, v5
	global_load_dwordx4 v[50:53], v5, s[64:65]
	global_load_dwordx4 v[54:57], v5, s[64:65] offset:16
	s_lshl_b32 s3, s1, 2
	s_add_u32 s70, s70, s3
	s_addc_u32 s71, s71, 0
	v_lshlrev_b32_e32 v6, 2, v0
	global_load_dword v58, v6, s[70:71]
	s_mul_i32 s3, s2, s9
	s_add_u32 s3, s3, s1
	s_lshl_b32 s3, s3, 1
	s_add_u32 s46, s66, s3
	s_addc_u32 s47, s67, 0
	s_mov_b32 s48, s9
	s_sub_u32 s49, s5, s2
	s_mov_b32 s50, s20
	s_waitcnt lgkmcnt(0)
	s_barrier
	ds_read_b32 v10, v4 offset:16640
	ds_read_b32 v11, v4 offset:16900
	ds_read_b32 v12, v4 offset:17160
	ds_read_b32 v13, v4 offset:17420
	ds_read_b32 v14, v4 offset:17680
	ds_read_b32 v15, v4 offset:17940
	ds_read_b32 v16, v4 offset:18200
	ds_read_b32 v17, v4 offset:18460
	v_mad_u32_u24 v7, v0, s38, v1
	v_lshlrev_b32_e32 v7, 1, v7
	s_waitcnt lgkmcnt(0)
	v_cvt_pk_bf16_f32 v18, v10, v11
	v_cvt_pk_bf16_f32 v19, v12, v13
	v_cvt_pk_bf16_f32 v20, v14, v15
	v_cvt_pk_bf16_f32 v21, v16, v17
	global_store_dwordx4 v7, v[18:21], s[36:37]
	s_add_u32 s35, s33, s68
	s_cmp_ge_u32 s35, 4032
	s_cbranch_scc1 .Lcv_a_exit
	s_add_u32 s34, s35, s21
	s_cmp_lt_u32 s34, 4032
	s_cselect_b32 s34, s34, s39
	s_waitcnt vmcnt(13)
	v_cmp_gt_i32_e32 vcc, s55, v1
	s_cmp_eq_u32 s56, 0
	s_cbranch_scc0 .Lcv_a_l2_hs
	v_mov_b32_e32 v68, 1.0

.Lcv_a_l2n_c:
	s_sub_u32 s0, s34, s8
	s_mul_hi_u32 s1, s0, s6
	s_mul_i32 s2, s1, s7
	s_sub_u32 s2, s0, s2
	s_lshl_b32 s1, s1, 6
	s_lshl_b32 s2, s2, 6
	s_mul_i32 s3, s1, s5
	s_lshl_b32 s3, s3, 2
	s_add_u32 s64, s64, s3
	s_addc_u32 s65, s65, 0
	v_add_u32_e32 v5, s2, v1
	s_sub_u32 s4, s5, 8
	v_min_u32_e32 v5, s4, v5
	v_mad_u32_u24 v5, v0, s5, v5
	v_lshlrev_b32_e32 v5, 2, v5
	global_load_dwordx4 v[60:63], v5, s[64:65]
	global_load_dwordx4 v[64:67], v5, s[64:65] offset:16
	s_lshl_b32 s3, s1, 2
	s_add_u32 s70, s70, s3
	s_addc_u32 s71, s71, 0
	v_lshlrev_b32_e32 v6, 2, v0
	global_load_dword v68, v6, s[70:71]
	s_mul_i32 s3, s2, s9
	s_add_u32 s3, s3, s1
	s_lshl_b32 s3, s3, 1
	s_add_u32 s52, s66, s3
	s_addc_u32 s53, s67, 0
	s_mov_b32 s54, s9
	s_sub_u32 s55, s5, s2
	s_mov_b32 s56, s20
	s_waitcnt lgkmcnt(0)
	s_barrier
	ds_read_b32 v10, v4 offset:0
	ds_read_b32 v11, v4 offset:260
	ds_read_b32 v12, v4 offset:520
	ds_read_b32 v13, v4 offset:780
	ds_read_b32 v14, v4 offset:1040
	ds_read_b32 v15, v4 offset:1300
	ds_read_b32 v16, v4 offset:1560
	ds_read_b32 v17, v4 offset:1820
	v_mad_u32_u24 v7, v0, s38, v1
	v_lshlrev_b32_e32 v7, 1, v7
	s_waitcnt lgkmcnt(0)
	v_cvt_pk_bf16_f32 v18, v10, v11
	v_cvt_pk_bf16_f32 v19, v12, v13
	v_cvt_pk_bf16_f32 v20, v14, v15
	v_cvt_pk_bf16_f32 v21, v16, v17
	global_store_dwordx4 v7, v[18:21], s[36:37]
	s_add_u32 s35, s33, s69
	s_cmp_ge_u32 s35, 4032
	s_cbranch_scc1 .Lcv_a_exit
	s_add_u32 s34, s35, s21
	s_cmp_lt_u32 s34, 4032
	s_cselect_b32 s34, s34, s39
	s_waitcnt vmcnt(13)
	v_cmp_gt_i32_e32 vcc, s61, v1
	s_cmp_eq_u32 s62, 0
	s_cbranch_scc0 .Lcv_a_l3_hs
	v_mov_b32_e32 v78, 1.0

.Lcv_a_l3n_c:
	s_sub_u32 s0, s34, s8
	s_mul_hi_u32 s1, s0, s6
	s_mul_i32 s2, s1, s7
	s_sub_u32 s2, s0, s2
	s_lshl_b32 s1, s1, 6
	s_lshl_b32 s2, s2, 6
	s_mul_i32 s3, s1, s5
	s_lshl_b32 s3, s3, 2
	s_add_u32 s64, s64, s3
	s_addc_u32 s65, s65, 0
	v_add_u32_e32 v5, s2, v1
	s_sub_u32 s4, s5, 8
	v_min_u32_e32 v5, s4, v5
	v_mad_u32_u24 v5, v0, s5, v5
	v_lshlrev_b32_e32 v5, 2, v5
	global_load_dwordx4 v[70:73], v5, s[64:65]
	global_load_dwordx4 v[74:77], v5, s[64:65] offset:16
	s_lshl_b32 s3, s1, 2
	s_add_u32 s70, s70, s3
	s_addc_u32 s71, s71, 0
	v_lshlrev_b32_e32 v6, 2, v0
	global_load_dword v78, v6, s[70:71]
	s_mul_i32 s3, s2, s9
	s_add_u32 s3, s3, s1
	s_lshl_b32 s3, s3, 1
	s_add_u32 s58, s66, s3
	s_addc_u32 s59, s67, 0
	s_mov_b32 s60, s9
	s_sub_u32 s61, s5, s2
	s_mov_b32 s62, s20
	s_waitcnt lgkmcnt(0)
	s_barrier
	ds_read_b32 v10, v4 offset:16640
	ds_read_b32 v11, v4 offset:16900
	ds_read_b32 v12, v4 offset:17160
	ds_read_b32 v13, v4 offset:17420
	ds_read_b32 v14, v4 offset:17680
	ds_read_b32 v15, v4 offset:17940
	ds_read_b32 v16, v4 offset:18200
	ds_read_b32 v17, v4 offset:18460
	v_mad_u32_u24 v7, v0, s38, v1
	v_lshlrev_b32_e32 v7, 1, v7
	s_waitcnt lgkmcnt(0)
	v_cvt_pk_bf16_f32 v18, v10, v11
	v_cvt_pk_bf16_f32 v19, v12, v13
	v_cvt_pk_bf16_f32 v20, v14, v15
	v_cvt_pk_bf16_f32 v21, v16, v17
	global_store_dwordx4 v7, v[18:21], s[36:37]
	s_add_u32 s33, s33, s21
	s_branch .Lcv_a_loop

.LBB0_164:
	s_andn2_b64 vcc, exec, s[30:31]
	s_cbranch_vccnz .LBB0_200
	s_waitcnt lgkmcnt(0)
	v_lshrrev_b32_e32 v0, 3, v204
	v_and_b32_e32 v1, 7, v204
	v_lshlrev_b32_e32 v1, 3, v1
	v_mul_u32_u24_e32 v2, 65, v0
	v_add_lshl_u32 v2, v2, v1, 2
	v_mul_u32_u24_e32 v4, 65, v1
	v_add_lshl_u32 v4, v4, v0, 2
	s_add_u32 s39, s97, 896
	s_mov_b32 s33, s39
	s_lshl_b32 s68, s22, 1
	s_mul_i32 s69, s22, 3
	s_lshl_b32 s21, s22, 2
	s_add_u32 s35, s33, 0
	s_cmp_lt_u32 s35, 4032
	s_cselect_b32 s35, s35, s39
	s_cmp_lt_u32 s35, 1152
	s_cbranch_scc0 .Lcv_b_p0_m1
	s_mov_b64 s[64:65], s[18:19]
	s_mov_b32 s5, 1024
	s_mov_b32 s6, 0x10000000
	s_mov_b32 s7, 16
	s_movk_i32 s8, 896
	s_add_u32 s66, s10, 0x700000
	s_addc_u32 s67, s11, 0
	s_movk_i32 s9, 1024
	s_mov_b32 s20, 0
	s_mov_b64 s[70:71], s[24:25]
	s_branch .Lcv_b_p0_c
